# sb_attention done-flags via ds_read/ds_write instead of serial flat loads; drop duplicate acquire+barrier after grid sync; P10 post_norm_b loop rewritten (gains preloaded, row loads batched and prefet
# speedup vs baseline: 1.1557x; 1.0193x over previous
.LBB0_361:
	s_or_b64 exec, exec, s[6:7]
	s_movk_i32 s40, 0x6000
	v_cmp_gt_i32_e32 vcc, s40, v200
	v_lshlrev_b32_e32 v72, 4, v199
	v_and_b32_e32 v236, 48, v196
	v_lshlrev_b32_e32 v74, 3, v199
	s_and_saveexec_b64 s[10:11], vcc
	s_cbranch_execz .LBB0_366
	s_mov_b32 s41, 0x2aaaaaab
	v_mul_hi_i32 v0, v200, s41
	v_ashrrev_i32_e32 v1, 4, v0
	v_lshrrev_b32_e32 v2, 31, v0
	v_add_u32_e32 v1, v1, v2
	v_ashrrev_i32_e32 v4, 31, v1
	v_lshrrev_b32_e32 v4, 26, v4
	s_movk_i32 s44, 0x60
	v_add_u32_e32 v4, v1, v4
	v_mul_lo_u32 v3, v1, s44
	v_and_b32_e32 v4, 0x3ffffc0, v4
	v_lshrrev_b32_e32 v0, 10, v0
	v_sub_u32_e32 v3, v200, v3
	v_sub_u32_e32 v1, v1, v4
	v_add_lshl_u32 v0, v0, v2, 12
	v_lshl_add_u32 v0, v1, 6, v0
	v_lshlrev_b32_e32 v2, 4, v3
	v_or_b32_e32 v0, v0, v198
	v_ashrrev_i32_e32 v3, 31, v2
	v_lshl_add_u64 v[2:3], v[2:3], 1, s[26:27]
	v_and_b32_e32 v4, 16, v196
	v_mov_b32_e32 v5, 0
	v_ashrrev_i32_e32 v1, 31, v0
	v_or_b32_e32 v8, 16, v0
	v_lshl_add_u64 v[2:3], v[2:3], 0, v[4:5]
	v_lshlrev_b64 v[6:7], 13, v[0:1]
	v_ashrrev_i32_e32 v9, 31, v8
	v_lshl_add_u64 v[6:7], v[2:3], 0, v[6:7]
	v_lshlrev_b64 v[8:9], 13, v[8:9]
	v_lshl_add_u64 v[8:9], v[2:3], 0, v[8:9]
	global_load_dwordx4 v[56:59], v[6:7], off
	global_load_dwordx4 v[60:63], v[8:9], off
	v_or_b32_e32 v6, 32, v0
	v_ashrrev_i32_e32 v7, 31, v6
	v_or_b32_e32 v0, 48, v0
	v_lshlrev_b64 v[6:7], 13, v[6:7]
	v_ashrrev_i32_e32 v1, 31, v0
	v_lshl_add_u64 v[6:7], v[2:3], 0, v[6:7]
	v_lshlrev_b64 v[0:1], 13, v[0:1]
	v_lshl_add_u64 v[0:1], v[2:3], 0, v[0:1]
	global_load_dwordx4 v[20:23], v[6:7], off
	global_load_dwordx4 v[16:19], v[0:1], off
	s_movk_i32 s78, 0x3900
	v_mad_u32_u24 v8, v201, s78, 0
	v_mov_b32_e32 v73, v5
	v_mov_b32_e32 v75, v5
	s_lshl_b32 s45, s34, 3
	v_mul_u32_u24_e32 v6, 0x50, v198
	v_mul_u32_u24_e32 v7, 0xa0, v199
	s_mov_b64 s[6:7], 0x1ac40000
	s_mov_b64 s[8:9], 0x1e900000
	s_mov_b64 s[38:39], 0x1e918000
	s_mov_b64 s[60:61], 0x1e918400
	s_mov_b64 s[64:65], 0x1e918800
	s_mov_b64 s[66:67], 0x1e918c00
	s_mov_b64 s[68:69], 0x1e919000
	s_mov_b64 s[70:71], 0x1e919400
	s_mov_b64 s[72:73], 0x1e919800
	s_mov_b64 s[76:77], 0x1e919c00
	v_lshl_add_u64 v[64:65], s[26:27], 0, v[4:5]
	v_add_u32_e32 v4, v8, v236
	v_lshl_add_u64 v[0:1], s[50:51], 0, v[74:75]
	v_lshl_add_u64 v[2:3], s[50:51], 0, v[72:73]
	s_add_i32 s75, s75, s45
	v_add_u32_e32 v67, v8, v7
	v_lshl_add_u64 v[68:69], v[0:1], 0, s[6:7]
	v_lshl_add_u64 v[70:71], v[2:3], 0, s[8:9]
	v_lshl_add_u64 v[76:77], v[2:3], 0, s[38:39]
	v_lshl_add_u64 v[78:79], v[2:3], 0, s[60:61]
	v_lshl_add_u64 v[80:81], v[2:3], 0, s[64:65]
	v_lshl_add_u64 v[82:83], v[2:3], 0, s[66:67]
	v_lshl_add_u64 v[84:85], v[2:3], 0, s[68:69]
	v_lshl_add_u64 v[86:87], v[2:3], 0, s[70:71]
	v_lshl_add_u64 v[88:89], v[2:3], 0, s[72:73]
	v_lshl_add_u64 v[90:91], v[2:3], 0, s[76:77]
	v_add_u32_e32 v73, v4, v6
	s_lshl_b32 s46, s34, 7
	s_mov_b64 s[22:23], 0
	s_movk_i32 s47, 0x5fff
	s_movk_i32 s56, 0xfa00
	s_movk_i32 s57, 0xffa0
	v_mov_b32_e32 v24, v200
	v_add_lshl_u32 v66, s75, v201, 4
	s_waitcnt vmcnt(3)
	v_mov_b64_e32 v[0:1], v[56:57]
	s_waitcnt vmcnt(2)
	v_mov_b64_e32 v[4:5], v[60:61]
	v_mov_b64_e32 v[2:3], v[58:59]
	v_mov_b64_e32 v[6:7], v[62:63]
	s_waitcnt vmcnt(1)
	v_mov_b64_e32 v[8:9], v[20:21]
	s_waitcnt vmcnt(0)
	v_mov_b64_e32 v[12:13], v[16:17]
	v_mov_b64_e32 v[10:11], v[22:23]
	v_mov_b64_e32 v[14:15], v[18:19]
	s_branch .LBB0_364

.LBB0_378:
	s_or_b64 exec, exec, s[6:7]
	v_lshrrev_b32_e32 v238, 4, v199
	s_movk_i32 s6, 0x3900
	v_mad_u32_u24 v116, v201, s6, 0
	v_lshlrev_b32_e32 v206, 3, v238
	v_lshlrev_b32_e32 v117, 2, v199
	v_lshlrev_b32_e32 v235, 2, v238
	v_lshlrev_b32_e32 v76, 1, v198
	s_and_saveexec_b64 s[6:7], vcc
	s_cbranch_execz .LBB0_391
	v_mov_b32_e32 v75, 0
	v_mov_b32_e32 v73, v75
	s_movk_i32 s8, 0x110
	v_mad_u32_u24 v6, v198, s8, v116
	v_lshl_add_u64 v[2:3], s[50:51], 0, v[72:73]
	s_mov_b64 s[8:9], 0x1e900000
	v_lshl_add_u64 v[78:79], v[2:3], 0, s[8:9]
	s_mov_b64 s[8:9], 0x1e918000
	v_lshl_add_u64 v[80:81], v[2:3], 0, s[8:9]
	s_mov_b64 s[8:9], 0x1e918400
	v_lshl_add_u64 v[82:83], v[2:3], 0, s[8:9]
	s_mov_b64 s[8:9], 0x1e918800
	v_lshl_add_u64 v[84:85], v[2:3], 0, s[8:9]
	s_mov_b64 s[8:9], 0x1e918c00
	v_lshl_add_u64 v[86:87], v[2:3], 0, s[8:9]
	s_mov_b64 s[8:9], 0x1e919000
	v_lshl_add_u64 v[88:89], v[2:3], 0, s[8:9]
	s_mov_b64 s[8:9], 0x1e919400
	v_lshl_add_u64 v[90:91], v[2:3], 0, s[8:9]
	s_mov_b64 s[8:9], 0x1e919800
	v_lshl_add_u64 v[92:93], v[2:3], 0, s[8:9]
	s_mov_b64 s[8:9], 0x1e919c00
	v_lshl_add_u64 v[94:95], v[2:3], 0, s[8:9]
	s_mov_b64 s[8:9], 0x1e9d8000
	v_mov_b32_e32 v77, v75
	v_lshl_add_u64 v[96:97], v[2:3], 0, s[8:9]
	v_lshl_add_u64 v[2:3], s[50:51], 0, v[76:77]
	s_mov_b64 s[8:9], 0x1b840000
	v_lshl_add_u64 v[98:99], v[2:3], 0, s[8:9]
	v_lshl_add_u64 v[2:3], s[48:49], 0, v[74:75]
	s_mov_b64 s[8:9], 0x14280000
	v_lshl_add_u64 v[100:101], v[2:3], 0, s[8:9]
	v_and_b32_e32 v2, 63, v196
	v_lshlrev_b32_e32 v74, 3, v2
	v_lshl_add_u64 v[2:3], s[50:51], 0, v[74:75]
	s_mov_b64 s[8:9], 0x1ac94004
	v_and_b32_e32 v0, 8, v206
	v_add_u32_e32 v1, v116, v236
	v_mul_u32_u24_e32 v4, 0x50, v198
	v_mul_u32_u24_e32 v5, 0xa0, v199
	v_lshl_add_u64 v[102:103], v[2:3], 0, s[8:9]
	s_mov_b64 s[8:9], 0x1ac40000
	s_lshl_b32 s44, s34, 3
	v_lshl_add_u64 v[104:105], v[2:3], 0, s[8:9]
	s_mov_b64 s[8:9], 0
	s_mov_b32 s45, 0x2aaaaaab
	s_movk_i32 s46, 0x60
	v_lshlrev_b32_e32 v106, 1, v0
	v_mov_b32_e32 v107, v75
	s_mov_b64 s[10:11], 0x60000
	s_mov_b32 s47, 0xc000
	s_mov_b64 s[22:23], 0xc000
	v_lshlrev_b32_e32 v74, 1, v198
	v_add_u32_e32 v73, v1, v4
	v_add_u32_e32 v77, v116, v5
	v_add_u32_e32 v118, v116, v117
	v_add_u32_e32 v119, v6, v236
	s_movk_i32 s56, 0xc00
	s_movk_i32 s57, 0x5fff
	v_mov_b32_e32 v120, v200
	s_branch .LBB0_381

.LBB0_406:
	s_or_b64 exec, exec, s[6:7]
	s_cmpk_gt_i32 s2, 0x185
	v_readfirstlane_b32 s64, v196
	s_cbranch_scc1 .LBB0_438
	s_ashr_i32 s6, s2, 31
	s_lshr_b32 s6, s6, 29
	s_add_i32 s9, s2, s6
	s_and_b32 s6, s9, -8
	s_sub_i32 s10, s2, s6
	s_cmp_gt_i32 s10, 5
	s_cbranch_scc0 .LBB0_409
	s_mul_i32 s6, s10, 48
	s_or_b32 s8, s6, 6
	s_cbranch_execz .LBB0_410
	s_branch .LBB0_411

.LBB0_473:
	s_or_b64 exec, exec, s[6:7]
	s_cmpk_lt_i32 s2, 0x208
	s_cselect_b64 s[28:29], -1, 0
	s_cmpk_gt_i32 s2, 0x207
	v_readfirstlane_b32 s3, v196
	s_cbranch_scc1 .LBB0_497
	s_ashr_i32 s6, s2, 31
	s_lshr_b32 s6, s6, 29
	s_add_i32 s6, s2, s6
	s_lshr_b32 s10, s3, 6
	s_ashr_i32 s7, s6, 3
	s_and_b32 s6, s6, -8
	s_lshr_b32 s23, s3, 8
	s_lshl_b32 s33, s10, 10
	s_sub_i32 s6, s2, s6
	s_cmp_lt_i32 s6, 0
	s_movk_i32 s35, 0x42
	s_cselect_b32 s8, s35, 0x41
	s_mul_i32 s6, s6, s8
	s_add_i32 s6, s6, s7
	s_ashr_i32 s7, s6, 31
	s_lshr_b32 s7, s7, 26
	s_add_i32 s7, s6, s7
	s_ashr_i32 s7, s7, 6
	s_lshl_b32 s8, s7, 3
	s_sub_i32 s9, 0x41, s8
	s_lshl_b32 s7, s7, 6
	s_min_u32 s9, s9, 8
	s_sub_i32 s11, s6, s7
	s_sext_i32_i8 s6, s11
	v_cvt_f32_ubyte0_e32 v1, s9
	v_cvt_f32_i32_e32 v0, s6
	v_rcp_iflag_f32_e32 v2, v1
	s_ashr_i32 s6, s6, 30
	s_or_b32 s22, s6, 1
	s_mov_b32 s79, 0
	v_mul_f32_e32 v2, v0, v2
	v_trunc_f32_e32 v2, v2
	v_fma_f32 v0, -v2, v1, v0
	v_cvt_i32_f32_e32 v2, v2
	v_cmp_ge_f32_e64 s[6:7], |v0|, v1
	s_and_b64 s[6:7], s[6:7], exec
	s_cselect_b32 s6, s22, 0
	v_readfirstlane_b32 s7, v2
	s_add_i32 s22, s7, s6
	s_mul_i32 s6, s22, s9
	s_sub_i32 s6, s11, s6
	s_sext_i32_i8 s6, s6
	s_add_i32 s58, s8, s6
	s_ashr_i32 s59, s58, 31
	s_lshl_b64 s[6:7], s[58:59], 20
	s_add_u32 s6, s24, s6
	s_addc_u32 s7, s25, s7
	s_bfe_i64 s[8:9], s[22:23], 0x80000
	s_lshl_b64 s[8:9], s[8:9], 20
	s_add_u32 s70, s12, s8
	s_addc_u32 s71, s13, s9
	s_add_i32 s59, s33, 0
	s_add_i32 m0, s59, 0x10000
	s_add_i32 s74, s59, 0x2000
	global_load_lds_dwordx4 v202, s[70:71]
	s_add_i32 m0, s59, 0x12000
	s_add_u32 s8, s70, 0x80000
	global_load_lds_dwordx4 v204, s[70:71]
	s_mov_b32 m0, s59
	s_addc_u32 s9, s71, 0
	global_load_lds_dwordx4 v202, s[6:7]
	s_mov_b32 m0, s74
	s_add_i32 s75, s59, 0x14000
	global_load_lds_dwordx4 v204, s[6:7]
	s_mov_b32 m0, s75
	s_add_i32 s76, s59, 0x16000
	global_load_lds_dwordx4 v202, s[8:9]
	s_mov_b32 m0, s76
	v_mov_b32_e32 v0, 0
	global_load_lds_dwordx4 v204, s[8:9]
	s_add_u32 s8, s6, 0x80000
	s_addc_u32 s9, s7, 0
	s_add_i32 s77, s59, 0x4000
	s_mov_b32 m0, s77
	s_add_i32 s78, s59, 0x6000
	global_load_lds_dwordx4 v202, s[8:9]
	s_mov_b32 m0, s78
	v_mov_b32_e32 v203, v0
	global_load_lds_dwordx4 v204, s[8:9]
	v_mov_b32_e32 v205, v0
	v_lshl_add_u64 v[8:9], s[70:71], 0, v[202:203]
	v_lshl_add_u64 v[6:7], s[70:71], 0, v[204:205]
	v_lshl_add_u64 v[4:5], s[6:7], 0, v[202:203]
	v_lshl_add_u64 v[2:3], s[6:7], 0, v[204:205]
	s_cmp_lg_u32 s23, 1
	s_mov_b64 s[8:9], 0x80000
	s_cbranch_scc1 .LBB0_476
	s_barrier

.LBB0_509:
	s_or_b64 exec, exec, s[6:7]
	s_movk_i32 s3, 0x4080
	v_cmp_gt_i32_e64 s[6:7], s3, v200
	s_and_saveexec_b64 s[8:9], s[6:7]
	s_cbranch_execz .LBB0_512
	v_mbcnt_hi_u32_b32 v1, -1, v232
	v_and_b32_e32 v2, 64, v1
	v_add_u32_e32 v2, 64, v2
	v_xor_b32_e32 v3, 32, v1
	v_cmp_lt_i32_e32 vcc, v3, v2
	v_and_b32_e32 v0, 0xfc, v226
	v_mov_b32_e32 v21, 0
	v_cndmask_b32_e32 v3, v1, v3, vcc
	v_lshlrev_b32_e32 v61, 2, v3
	v_xor_b32_e32 v3, 16, v1
	v_cmp_lt_i32_e32 vcc, v3, v2
	v_lshlrev_b32_e32 v20, 2, v0
	v_or_b32_e32 v4, 0x500, v0
	v_cndmask_b32_e32 v3, v1, v3, vcc
	v_lshlrev_b32_e32 v62, 2, v3
	v_xor_b32_e32 v3, 8, v1
	v_cmp_lt_i32_e32 vcc, v3, v2
	v_lshl_add_u64 v[22:23], s[14:15], 0, v[20:21]
	v_or_b32_e32 v6, 0x600, v0
	v_cndmask_b32_e32 v3, v1, v3, vcc
	v_lshlrev_b32_e32 v63, 2, v3
	v_xor_b32_e32 v3, 4, v1
	v_cmp_lt_i32_e32 vcc, v3, v2
	v_or_b32_e32 v8, 0x700, v0
	s_lshl_b32 s3, s34, 3
	v_cndmask_b32_e32 v3, v1, v3, vcc
	v_lshlrev_b32_e32 v64, 2, v3
	v_xor_b32_e32 v3, 2, v1
	v_cmp_lt_i32_e32 vcc, v3, v2
	s_mov_b64 s[10:11], 0
	s_movk_i32 s12, 0x4000
	v_cndmask_b32_e32 v3, v1, v3, vcc
	v_lshlrev_b32_e32 v65, 2, v3
	v_xor_b32_e32 v3, 1, v1
	v_cmp_lt_i32_e32 vcc, v3, v2
	v_or_b32_e32 v2, 0x400, v0
	v_lshlrev_b32_e32 v20, 2, v2
	v_lshl_add_u64 v[24:25], s[14:15], 0, v[20:21]
	v_lshlrev_b32_e32 v20, 2, v4
	v_lshl_add_u64 v[26:27], s[14:15], 0, v[20:21]
	v_lshlrev_b32_e32 v20, 2, v6
	v_lshl_add_u64 v[28:29], s[14:15], 0, v[20:21]
	v_lshlrev_b32_e32 v20, 2, v8
	v_cndmask_b32_e32 v1, v1, v3, vcc
	v_lshl_add_u64 v[30:31], s[14:15], 0, v[20:21]
	v_lshlrev_b32_e32 v20, 1, v0
	v_lshlrev_b32_e32 v66, 2, v1
	v_lshl_add_u64 v[32:33], s[26:27], 0, v[20:21]
	v_lshl_add_u64 v[34:35], s[24:25], 0, v[20:21]
	v_mov_b32_e32 v67, s19
	v_mov_b32_e32 v68, s17
	v_mov_b32_e32 v69, s18
	v_mov_b32_e32 v70, s16
	v_mov_b32_e32 v71, 0x358637bd
	s_mov_b32 s13, 0x800000
	v_lshlrev_b32_e32 v20, 2, v0
	v_lshlrev_b32_e32 v36, 2, v2
	v_mov_b32_e32 v37, v21
	v_lshlrev_b32_e32 v38, 2, v4
	v_mov_b32_e32 v39, v21
	v_lshlrev_b32_e32 v40, 2, v6
	v_mov_b32_e32 v41, v21
	v_lshlrev_b32_e32 v42, 2, v8
	v_mov_b32_e32 v43, v21
	s_movk_i32 s14, 0x407f
	v_mov_b32_e32 v44, v200

.LBB0_524:
	s_or_b64 exec, exec, s[8:9]
	s_cmpk_lt_i32 s2, 0x71c
	s_cselect_b64 s[12:13], -1, 0
	s_cmpk_gt_i32 s2, 0x71b
	v_readfirstlane_b32 s35, v196
	s_cbranch_scc1 .LBB0_527
	s_ashr_i32 s3, s2, 31
	s_lshr_b32 s3, s3, 29
	s_add_i32 s3, s2, s3
	s_and_b32 s8, s3, -8
	s_sub_i32 s10, s2, s8
	s_cmp_gt_i32 s10, 3
	s_cbranch_scc0 .LBB0_528
	s_mul_i32 s8, s10, 0xe3
	s_add_i32 s11, s8, 4
	s_cbranch_execz .LBB0_529
	s_branch .LBB0_530

.LBB0_858:
	s_or_b64 exec, exec, s[8:9]
	s_cmpk_lt_i32 s2, 0x660
	s_cbranch_scc1 .LBB0_860
	v_add_u32_e32 v0, 0x200, v196
	v_lshrrev_b32_e32 v83, 4, v0
	v_mul_u32_u24_e32 v84, 0x110, v198
	v_mul_u32_u24_e32 v79, 0x110, v234
	v_mul_u32_u24_e32 v82, 0x110, v83
	v_mul_u32_u24_e32 v80, 0x120, v234
	v_mul_u32_u24_e32 v81, 0x120, v83
	v_and_b32_e32 v85, 24, v239
	s_cbranch_execz .LBB0_861
	s_branch .LBB0_881

.LBB0_870:
	s_or_b64 exec, exec, s[18:19]
	v_mov_b32_e32 v99, 0x8c00
	s_waitcnt lgkmcnt(0)
	s_barrier
	ds_read_b128 v[100:103], v99
	ds_read_b128 v[64:67], v99 offset:16
	v_subrev_co_u32_e32 v98, vcc, 1, v98
	s_sub_i32 s60, s60, 64
	s_waitcnt lgkmcnt(0)
	v_and_b32_e32 v99, v100, v101
	v_bitop3_b32 v99, v99, v102, v103 bitop3:0x80
	v_bitop3_b32 v99, v99, v64, v65 bitop3:0x80
	v_bitop3_b32 v64, v99, v66, v67 bitop3:0x80
	v_and_b32_e32 v64, 1, v64
	v_cmp_eq_u32_e64 s[18:19], 1, v64
	s_or_b64 s[18:19], vcc, s[18:19]
	s_and_b64 s[18:19], exec, s[18:19]
	s_or_b64 s[44:45], s[18:19], s[44:45]
	s_andn2_b64 exec, exec, s[44:45]
	s_cbranch_execz .LBB0_879

.LBB0_877:
	s_or_b64 exec, exec, s[46:47]
	s_and_saveexec_b64 s[18:19], s[14:15]
	s_cbranch_execz .LBB0_870
	v_cndmask_b32_e64 v64, 0, 1, s[20:21]
	ds_write_b32 v70, v64
	s_branch .LBB0_870
.LBB0_879:
	s_waitcnt vmcnt(0)
	s_or_b64 exec, exec, s[44:45]
	s_and_saveexec_b64 s[20:21], s[16:17]
	s_cbranch_execz .LBB0_862
	v_add_u32_e32 v50, s59, v90
	v_lshl_or_b32 v48, s58, 7, v198
	v_ashrrev_i32_e32 v51, 31, v50
	v_lshlrev_b64 v[52:53], 13, v[50:51]
	v_ashrrev_i32_e32 v49, 31, v48
	v_add_u32_e32 v62, 1, v50
	v_lshl_add_u64 v[52:53], s[26:27], 0, v[52:53]
	v_lshlrev_b64 v[60:61], 1, v[48:49]
	v_ashrrev_i32_e32 v63, 31, v62
	v_lshl_add_u64 v[66:67], v[52:53], 0, v[60:61]
	v_lshlrev_b64 v[52:53], 13, v[62:63]
	v_add_u32_e32 v54, 2, v50
	v_lshl_add_u64 v[52:53], s[26:27], 0, v[52:53]
	v_ashrrev_i32_e32 v55, 31, v54
	v_lshl_add_u64 v[74:75], v[52:53], 0, v[60:61]
	v_lshlrev_b64 v[52:53], 13, v[54:55]
	global_load_ushort v49, v[66:67], off offset:3072
	global_load_ushort v78, v[74:75], off offset:3072
	v_lshl_add_u64 v[52:53], s[26:27], 0, v[52:53]
	v_lshl_add_u64 v[76:77], v[52:53], 0, v[60:61]
	global_load_ushort v98, v[76:77], off offset:3072
	v_add_u32_e32 v56, 3, v50
	v_ashrrev_i32_e32 v57, 31, v56
	v_lshlrev_b64 v[96:97], 13, v[56:57]
	v_lshl_add_u64 v[96:97], s[26:27], 0, v[96:97]
	v_lshl_add_u64 v[58:59], s[24:25], 0, v[60:61]
	v_lshl_add_u64 v[60:61], v[96:97], 0, v[60:61]
	global_load_ushort v73, v[66:67], off offset:3104
	global_load_ushort v96, v[66:67], off offset:3136
	global_load_ushort v97, v[66:67], off offset:3168
	global_load_ushort v99, v[66:67], off offset:3200
	global_load_ushort v100, v[66:67], off offset:3232
	global_load_ushort v101, v[66:67], off offset:3264
	global_load_ushort v102, v[66:67], off offset:3296
	global_load_ushort v105, v[60:61], off offset:3072
	global_load_ushort v106, v[74:75], off offset:3104
	global_load_ushort v107, v[74:75], off offset:3136
	global_load_ushort v108, v[74:75], off offset:3168
	global_load_ushort v109, v[74:75], off offset:3200
	global_load_ushort v104, v[74:75], off offset:3232
	global_load_ushort v103, v[74:75], off offset:3264
	global_load_ushort v66, v[74:75], off offset:3296
	s_nop 0
	global_load_ushort v75, v[76:77], off offset:3104
	global_load_ushort v110, v[76:77], off offset:3136
	global_load_ushort v111, v[76:77], off offset:3168
	global_load_ushort v112, v[76:77], off offset:3200
	global_load_ushort v113, v[76:77], off offset:3232
	global_load_ushort v74, v[76:77], off offset:3264
	global_load_ushort v67, v[76:77], off offset:3296
	v_lshlrev_b64 v[52:53], 12, v[50:51]
	v_lshlrev_b64 v[50:51], 12, v[62:63]
	v_lshl_add_u64 v[64:65], v[58:59], 0, v[52:53]
	v_lshl_add_u64 v[62:63], v[58:59], 0, v[50:51]
	v_lshlrev_b64 v[54:55], 12, v[54:55]
	v_lshlrev_b64 v[56:57], 12, v[56:57]
	s_waitcnt vmcnt(24)
	v_lshlrev_b32_e32 v49, 16, v49
	v_mul_f32_e32 v76, 0xbfb8aa3b, v49
	s_waitcnt vmcnt(23)
	v_lshlrev_b32_e32 v77, 16, v78
	v_exp_f32_e32 v76, v76
	s_waitcnt vmcnt(22)
	v_lshlrev_b32_e32 v78, 16, v98
	v_mul_f32_e32 v98, 0xbfb8aa3b, v77
	v_mul_f32_e32 v114, 0xbfb8aa3b, v78
	v_exp_f32_e32 v98, v98
	v_exp_f32_e32 v114, v114
	v_add_f32_e32 v76, 1.0, v76
	v_div_scale_f32 v115, s[16:17], v76, v76, v49
	v_add_f32_e32 v98, 1.0, v98
	v_add_f32_e32 v114, 1.0, v114
	v_rcp_f32_e32 v117, v115
	v_div_scale_f32 v118, s[16:17], v98, v98, v77
	v_div_scale_f32 v120, s[18:19], v114, v114, v78
	v_rcp_f32_e32 v122, v118
	v_rcp_f32_e32 v123, v120
	v_fma_f32 v124, -v115, v117, 1.0
	v_div_scale_f32 v116, vcc, v49, v76, v49
	v_fmac_f32_e32 v117, v124, v117
	v_fma_f32 v124, -v118, v122, 1.0
	v_div_scale_f32 v119, s[16:17], v77, v98, v77
	v_fma_f32 v125, -v120, v123, 1.0
	v_mul_f32_e32 v126, v116, v117
	v_fmac_f32_e32 v122, v124, v122
	v_fmac_f32_e32 v123, v125, v123
	v_fma_f32 v124, -v115, v126, v116
	v_mul_f32_e32 v125, v119, v122
	v_fmac_f32_e32 v126, v124, v117
	v_fma_f32 v124, -v118, v125, v119
	v_fma_f32 v115, -v115, v126, v116
	v_fmac_f32_e32 v125, v124, v122
	v_div_fmas_f32 v115, v115, v117, v126
	v_fma_f32 v116, -v118, v125, v119
	s_mov_b64 vcc, s[16:17]
	v_div_fixup_f32 v49, v115, v76, v49
	v_div_fmas_f32 v76, v116, v122, v125
	v_mul_f32_e32 v44, v44, v49
	v_div_fixup_f32 v49, v76, v98, v77
	v_cvt_pk_bf16_f32 v44, v44, s0
	v_mul_f32_e32 v45, v45, v49
	global_store_short v[64:65], v44, off
	v_cvt_pk_bf16_f32 v44, v45, s0
	global_store_short v[62:63], v44, off
	global_load_ushort v63, v[60:61], off offset:3104
	s_nop 0
	global_load_ushort v64, v[60:61], off offset:3136
	global_load_ushort v65, v[60:61], off offset:3168
	global_load_ushort v76, v[60:61], off offset:3200
	global_load_ushort v77, v[60:61], off offset:3232
	global_load_ushort v62, v[60:61], off offset:3264
	global_load_ushort v49, v[60:61], off offset:3296
	s_waitcnt vmcnt(23)
	v_lshlrev_b32_e32 v60, 16, v105
	v_div_scale_f32 v121, s[18:19], v78, v114, v78
	v_mul_f32_e32 v45, 0xbfb8aa3b, v60
	v_mul_f32_e32 v127, v121, v123
	v_exp_f32_e32 v45, v45
	v_fma_f32 v128, -v120, v127, v121
	v_fmac_f32_e32 v127, v128, v123
	v_fma_f32 v44, -v120, v127, v121
	s_mov_b64 vcc, s[18:19]
	v_div_fmas_f32 v44, v44, v123, v127
	v_add_f32_e32 v61, 1.0, v45
	v_div_fixup_f32 v44, v44, v114, v78
	v_div_scale_f32 v78, s[16:17], v61, v61, v60
	v_rcp_f32_e32 v98, v78
	v_mul_f32_e32 v44, v46, v44
	v_cvt_pk_bf16_f32 v46, v44, s0
	v_lshl_add_u64 v[44:45], v[58:59], 0, v[54:55]
	global_store_short v[44:45], v46, off
	v_fma_f32 v44, -v78, v98, 1.0
	v_fmac_f32_e32 v98, v44, v98
	v_div_scale_f32 v44, vcc, v60, v61, v60
	v_mul_f32_e32 v45, v44, v98
	v_fma_f32 v46, -v78, v45, v44
	v_fmac_f32_e32 v45, v46, v98
	v_fma_f32 v44, -v78, v45, v44
	v_div_fmas_f32 v44, v44, v98, v45
	v_div_fixup_f32 v44, v44, v61, v60
	v_lshlrev_b32_e32 v60, 16, v73
	v_mul_f32_e32 v45, 0xbfb8aa3b, v60
	v_exp_f32_e32 v46, v45
	v_mul_f32_e32 v44, v47, v44
	v_cvt_pk_bf16_f32 v47, v44, s0
	v_lshl_add_u64 v[44:45], v[58:59], 0, v[56:57]
	v_add_f32_e32 v58, 1.0, v46
	v_div_scale_f32 v59, s[16:17], v58, v58, v60
	v_rcp_f32_e32 v61, v59
	global_store_short v[44:45], v47, off
	v_or_b32_e32 v46, 16, v48
	v_ashrrev_i32_e32 v47, 31, v46
	v_fma_f32 v44, -v59, v61, 1.0
	v_fmac_f32_e32 v61, v44, v61
	v_div_scale_f32 v44, vcc, v60, v58, v60
	v_mul_f32_e32 v45, v44, v61
	v_fma_f32 v73, -v59, v45, v44
	v_fmac_f32_e32 v45, v73, v61
	v_fma_f32 v44, -v59, v45, v44
	v_div_fmas_f32 v44, v44, v61, v45
	v_div_fixup_f32 v44, v44, v58, v60
	s_waitcnt vmcnt(24)
	v_lshlrev_b32_e32 v58, 16, v106
	v_mul_f32_e32 v45, 0xbfb8aa3b, v58
	v_exp_f32_e32 v59, v45
	v_mul_f32_e32 v40, v40, v44
	v_lshl_add_u64 v[44:45], s[24:25], 0, v[52:53]
	v_lshlrev_b64 v[52:53], 1, v[46:47]
	v_add_f32_e32 v59, 1.0, v59
	v_div_scale_f32 v60, s[16:17], v59, v59, v58
	v_rcp_f32_e32 v61, v60
	v_cvt_pk_bf16_f32 v40, v40, s0
	v_lshl_add_u64 v[46:47], v[44:45], 0, v[52:53]
	global_store_short v[46:47], v40, off
	v_fma_f32 v40, -v60, v61, 1.0
	v_fmac_f32_e32 v61, v40, v61
	v_div_scale_f32 v40, vcc, v58, v59, v58
	v_mul_f32_e32 v46, v40, v61
	v_fma_f32 v47, -v60, v46, v40
	v_fmac_f32_e32 v46, v47, v61
	v_fma_f32 v40, -v60, v46, v40
	s_waitcnt vmcnt(18)
	v_lshlrev_b32_e32 v60, 16, v75
	v_div_fmas_f32 v40, v40, v61, v46
	v_mul_f32_e32 v46, 0xbfb8aa3b, v60
	v_exp_f32_e32 v46, v46
	v_div_fixup_f32 v40, v40, v59, v58
	v_mul_f32_e32 v40, v41, v40
	v_cvt_pk_bf16_f32 v58, v40, s0
	v_add_f32_e32 v59, 1.0, v46
	v_div_scale_f32 v61, s[16:17], v59, v59, v60
	v_rcp_f32_e32 v73, v61
	v_lshl_add_u64 v[40:41], s[24:25], 0, v[50:51]
	v_lshl_add_u64 v[46:47], v[40:41], 0, v[52:53]
	global_store_short v[46:47], v58, off
	v_fma_f32 v46, -v61, v73, 1.0
	v_fmac_f32_e32 v73, v46, v73
	v_div_scale_f32 v46, vcc, v60, v59, v60
	v_mul_f32_e32 v47, v46, v73
	v_fma_f32 v50, -v61, v47, v46
	v_fmac_f32_e32 v47, v50, v73
	v_fma_f32 v46, -v61, v47, v46
	s_waitcnt vmcnt(10)
	v_lshlrev_b32_e32 v58, 16, v63
	v_div_fmas_f32 v46, v46, v73, v47
	v_mul_f32_e32 v47, 0xbfb8aa3b, v58
	v_exp_f32_e32 v47, v47
	v_div_fixup_f32 v46, v46, v59, v60
	v_mul_f32_e32 v42, v42, v46
	v_cvt_pk_bf16_f32 v42, v42, s0
	v_add_f32_e32 v59, 1.0, v47
	v_div_scale_f32 v60, s[16:17], v59, v59, v58
	v_rcp_f32_e32 v61, v60
	v_lshl_add_u64 v[46:47], s[24:25], 0, v[54:55]
	v_lshl_add_u64 v[50:51], v[46:47], 0, v[52:53]
	global_store_short v[50:51], v42, off
	v_fma_f32 v42, -v60, v61, 1.0
	v_fmac_f32_e32 v61, v42, v61
	v_div_scale_f32 v42, vcc, v58, v59, v58
	v_mul_f32_e32 v50, v42, v61
	v_fma_f32 v51, -v60, v50, v42
	v_fmac_f32_e32 v50, v51, v61
	v_fma_f32 v42, -v60, v50, v42
	v_div_fmas_f32 v42, v42, v61, v50
	v_div_fixup_f32 v42, v42, v59, v58
	v_lshlrev_b32_e32 v54, 16, v96
	v_mul_f32_e32 v42, v43, v42
	v_mul_f32_e32 v43, 0xbfb8aa3b, v54
	v_exp_f32_e32 v55, v43
	v_cvt_pk_bf16_f32 v58, v42, s0
	v_lshl_add_u64 v[42:43], s[24:25], 0, v[56:57]
	v_lshl_add_u64 v[50:51], v[42:43], 0, v[52:53]
	v_add_f32_e32 v52, 1.0, v55
	v_div_scale_f32 v53, s[16:17], v52, v52, v54
	v_rcp_f32_e32 v55, v53
	global_store_short v[50:51], v58, off
	v_or_b32_e32 v50, 32, v48
	v_ashrrev_i32_e32 v51, 31, v50
	v_fma_f32 v56, -v53, v55, 1.0
	v_fmac_f32_e32 v55, v56, v55
	v_div_scale_f32 v56, vcc, v54, v52, v54
	v_mul_f32_e32 v57, v56, v55
	v_fma_f32 v58, -v53, v57, v56
	v_fmac_f32_e32 v57, v58, v55
	v_fma_f32 v53, -v53, v57, v56
	v_div_fmas_f32 v53, v53, v55, v57
	v_lshlrev_b32_e32 v55, 16, v107
	v_mul_f32_e32 v56, 0xbfb8aa3b, v55
	v_exp_f32_e32 v56, v56
	v_div_fixup_f32 v52, v53, v52, v54
	v_mul_f32_e32 v36, v36, v52
	v_lshlrev_b64 v[50:51], 1, v[50:51]
	v_add_f32_e32 v54, 1.0, v56
	v_div_scale_f32 v56, s[16:17], v54, v54, v55
	v_rcp_f32_e32 v57, v56
	v_cvt_pk_bf16_f32 v36, v36, s0
	v_lshl_add_u64 v[52:53], v[44:45], 0, v[50:51]
	global_store_short v[52:53], v36, off
	v_fma_f32 v36, -v56, v57, 1.0
	v_fmac_f32_e32 v57, v36, v57
	v_div_scale_f32 v36, vcc, v55, v54, v55
	v_mul_f32_e32 v52, v36, v57
	v_fma_f32 v53, -v56, v52, v36
	v_fmac_f32_e32 v52, v53, v57
	v_lshlrev_b32_e32 v53, 16, v110
	v_fma_f32 v36, -v56, v52, v36
	v_mul_f32_e32 v56, 0xbfb8aa3b, v53
	v_exp_f32_e32 v56, v56
	v_div_fmas_f32 v36, v36, v57, v52
	v_div_fixup_f32 v36, v36, v54, v55
	v_mul_f32_e32 v36, v37, v36
	v_add_f32_e32 v52, 1.0, v56
	v_div_scale_f32 v54, s[16:17], v52, v52, v53
	v_rcp_f32_e32 v55, v54
	v_cvt_pk_bf16_f32 v56, v36, s0
	v_lshl_add_u64 v[36:37], v[40:41], 0, v[50:51]
	global_store_short v[36:37], v56, off
	v_fma_f32 v36, -v54, v55, 1.0
	v_fmac_f32_e32 v55, v36, v55
	v_div_scale_f32 v36, vcc, v53, v52, v53
	v_mul_f32_e32 v37, v36, v55
	v_fma_f32 v56, -v54, v37, v36
	v_fmac_f32_e32 v37, v56, v55
	v_fma_f32 v36, -v54, v37, v36
	s_waitcnt vmcnt(13)
	v_lshlrev_b32_e32 v54, 16, v64
	v_mul_f32_e32 v56, 0xbfb8aa3b, v54
	v_exp_f32_e32 v56, v56
	v_div_fmas_f32 v36, v36, v55, v37
	v_div_fixup_f32 v36, v36, v52, v53
	v_mul_f32_e32 v36, v38, v36
	v_add_f32_e32 v38, 1.0, v56
	v_div_scale_f32 v52, s[16:17], v38, v38, v54
	v_rcp_f32_e32 v53, v52
	v_cvt_pk_bf16_f32 v55, v36, s0
	v_lshl_add_u64 v[36:37], v[46:47], 0, v[50:51]
	global_store_short v[36:37], v55, off
	v_fma_f32 v36, -v52, v53, 1.0
	v_fmac_f32_e32 v53, v36, v53
	v_div_scale_f32 v36, vcc, v54, v38, v54
	v_mul_f32_e32 v37, v36, v53
	v_fma_f32 v55, -v52, v37, v36
	v_fmac_f32_e32 v37, v55, v53
	v_fma_f32 v36, -v52, v37, v36
	v_div_fmas_f32 v36, v36, v53, v37
	v_div_fixup_f32 v36, v36, v38, v54
	v_lshlrev_b32_e32 v38, 16, v97
	v_mul_f32_e32 v37, 0xbfb8aa3b, v38
	v_exp_f32_e32 v52, v37
	v_mul_f32_e32 v36, v39, v36
	v_cvt_pk_bf16_f32 v39, v36, s0
	v_lshl_add_u64 v[36:37], v[42:43], 0, v[50:51]
	v_add_f32_e32 v50, 1.0, v52
	v_div_scale_f32 v51, s[16:17], v50, v50, v38
	v_rcp_f32_e32 v52, v51
	global_store_short v[36:37], v39, off
	v_or_b32_e32 v36, 48, v48
	v_ashrrev_i32_e32 v37, 31, v36
	v_fma_f32 v39, -v51, v52, 1.0
	v_fmac_f32_e32 v52, v39, v52
	v_div_scale_f32 v39, vcc, v38, v50, v38
	v_mul_f32_e32 v53, v39, v52
	v_fma_f32 v54, -v51, v53, v39
	v_fmac_f32_e32 v53, v54, v52
	v_fma_f32 v39, -v51, v53, v39
	v_lshlrev_b32_e32 v51, 16, v108
	v_div_fmas_f32 v39, v39, v52, v53
	v_mul_f32_e32 v52, 0xbfb8aa3b, v51
	v_exp_f32_e32 v52, v52
	v_div_fixup_f32 v38, v39, v50, v38
	v_mul_f32_e32 v32, v32, v38
	v_lshlrev_b64 v[36:37], 1, v[36:37]
	v_add_f32_e32 v50, 1.0, v52
	v_div_scale_f32 v52, s[16:17], v50, v50, v51
	v_rcp_f32_e32 v53, v52
	v_cvt_pk_bf16_f32 v32, v32, s0
	v_lshl_add_u64 v[38:39], v[44:45], 0, v[36:37]
	global_store_short v[38:39], v32, off
	v_fma_f32 v32, -v52, v53, 1.0
	v_fmac_f32_e32 v53, v32, v53
	v_div_scale_f32 v32, vcc, v51, v50, v51
	v_mul_f32_e32 v38, v32, v53
	v_fma_f32 v39, -v52, v38, v32
	v_fmac_f32_e32 v38, v39, v53
	v_lshlrev_b32_e32 v39, 16, v111
	v_fma_f32 v32, -v52, v38, v32
	v_mul_f32_e32 v52, 0xbfb8aa3b, v39
	v_exp_f32_e32 v52, v52
	v_div_fmas_f32 v32, v32, v53, v38
	v_div_fixup_f32 v32, v32, v50, v51
	v_mul_f32_e32 v32, v33, v32
	v_add_f32_e32 v38, 1.0, v52
	v_div_scale_f32 v50, s[16:17], v38, v38, v39
	v_rcp_f32_e32 v51, v50
	v_cvt_pk_bf16_f32 v52, v32, s0
	v_lshl_add_u64 v[32:33], v[40:41], 0, v[36:37]
	global_store_short v[32:33], v52, off
	v_fma_f32 v32, -v50, v51, 1.0
	v_fmac_f32_e32 v51, v32, v51
	v_div_scale_f32 v32, vcc, v39, v38, v39
	v_mul_f32_e32 v33, v32, v51
	v_fma_f32 v52, -v50, v33, v32
	v_fmac_f32_e32 v33, v52, v51
	v_fma_f32 v32, -v50, v33, v32
	s_waitcnt vmcnt(16)
	v_lshlrev_b32_e32 v50, 16, v65
	v_mul_f32_e32 v52, 0xbfb8aa3b, v50
	v_exp_f32_e32 v52, v52
	v_div_fmas_f32 v32, v32, v51, v33
	v_div_fixup_f32 v32, v32, v38, v39
	v_mul_f32_e32 v32, v34, v32
	v_add_f32_e32 v34, 1.0, v52
	v_div_scale_f32 v38, s[16:17], v34, v34, v50
	v_rcp_f32_e32 v39, v38
	v_cvt_pk_bf16_f32 v51, v32, s0
	v_lshl_add_u64 v[32:33], v[46:47], 0, v[36:37]
	global_store_short v[32:33], v51, off
	v_fma_f32 v32, -v38, v39, 1.0
	v_fmac_f32_e32 v39, v32, v39
	v_div_scale_f32 v32, vcc, v50, v34, v50
	v_mul_f32_e32 v33, v32, v39
	v_fma_f32 v51, -v38, v33, v32
	v_fmac_f32_e32 v33, v51, v39
	v_fma_f32 v32, -v38, v33, v32
	v_div_fmas_f32 v32, v32, v39, v33
	v_div_fixup_f32 v32, v32, v34, v50
	v_lshlrev_b32_e32 v34, 16, v99
	v_mul_f32_e32 v33, 0xbfb8aa3b, v34
	v_exp_f32_e32 v38, v33
	v_mul_f32_e32 v32, v35, v32
	v_cvt_pk_bf16_f32 v35, v32, s0
	v_lshl_add_u64 v[32:33], v[42:43], 0, v[36:37]
	v_add_f32_e32 v36, 1.0, v38
	v_div_scale_f32 v37, s[16:17], v36, v36, v34
	v_rcp_f32_e32 v38, v37
	global_store_short v[32:33], v35, off
	v_or_b32_e32 v32, 64, v48
	v_ashrrev_i32_e32 v33, 31, v32
	v_fma_f32 v35, -v37, v38, 1.0
	v_fmac_f32_e32 v38, v35, v38
	v_div_scale_f32 v35, vcc, v34, v36, v34
	v_mul_f32_e32 v39, v35, v38
	v_fma_f32 v50, -v37, v39, v35
	v_fmac_f32_e32 v39, v50, v38
	v_fma_f32 v35, -v37, v39, v35
	v_lshlrev_b32_e32 v37, 16, v109
	v_div_fmas_f32 v35, v35, v38, v39
	v_mul_f32_e32 v38, 0xbfb8aa3b, v37
	v_exp_f32_e32 v38, v38
	v_div_fixup_f32 v34, v35, v36, v34
	v_mul_f32_e32 v28, v28, v34
	v_lshlrev_b64 v[32:33], 1, v[32:33]
	v_add_f32_e32 v36, 1.0, v38
	v_div_scale_f32 v38, s[16:17], v36, v36, v37
	v_rcp_f32_e32 v39, v38
	v_cvt_pk_bf16_f32 v28, v28, s0
	v_lshl_add_u64 v[34:35], v[44:45], 0, v[32:33]
	global_store_short v[34:35], v28, off
	v_fma_f32 v28, -v38, v39, 1.0
	v_fmac_f32_e32 v39, v28, v39
	v_div_scale_f32 v28, vcc, v37, v36, v37
	v_mul_f32_e32 v34, v28, v39
	v_fma_f32 v35, -v38, v34, v28
	v_fmac_f32_e32 v34, v35, v39
	v_lshlrev_b32_e32 v35, 16, v112
	v_fma_f32 v28, -v38, v34, v28
	v_mul_f32_e32 v38, 0xbfb8aa3b, v35
	v_exp_f32_e32 v38, v38
	v_div_fmas_f32 v28, v28, v39, v34
	v_div_fixup_f32 v28, v28, v36, v37
	v_mul_f32_e32 v28, v29, v28
	v_add_f32_e32 v34, 1.0, v38
	v_div_scale_f32 v36, s[16:17], v34, v34, v35
	v_rcp_f32_e32 v37, v36
	v_cvt_pk_bf16_f32 v38, v28, s0
	v_lshl_add_u64 v[28:29], v[40:41], 0, v[32:33]
	global_store_short v[28:29], v38, off
	v_fma_f32 v28, -v36, v37, 1.0
	v_fmac_f32_e32 v37, v28, v37
	v_div_scale_f32 v28, vcc, v35, v34, v35
	v_mul_f32_e32 v29, v28, v37
	v_fma_f32 v38, -v36, v29, v28
	v_fmac_f32_e32 v29, v38, v37
	v_fma_f32 v28, -v36, v29, v28
	s_waitcnt vmcnt(19)
	v_lshlrev_b32_e32 v36, 16, v76
	v_mul_f32_e32 v38, 0xbfb8aa3b, v36
	v_exp_f32_e32 v38, v38
	v_div_fmas_f32 v28, v28, v37, v29
	v_div_fixup_f32 v28, v28, v34, v35
	v_mul_f32_e32 v28, v30, v28
	v_add_f32_e32 v30, 1.0, v38
	v_div_scale_f32 v34, s[16:17], v30, v30, v36
	v_rcp_f32_e32 v35, v34
	v_cvt_pk_bf16_f32 v37, v28, s0
	v_lshl_add_u64 v[28:29], v[46:47], 0, v[32:33]
	global_store_short v[28:29], v37, off
	v_fma_f32 v28, -v34, v35, 1.0
	v_fmac_f32_e32 v35, v28, v35
	v_div_scale_f32 v28, vcc, v36, v30, v36
	v_mul_f32_e32 v29, v28, v35
	v_fma_f32 v37, -v34, v29, v28
	v_fmac_f32_e32 v29, v37, v35
	v_fma_f32 v28, -v34, v29, v28
	v_div_fmas_f32 v28, v28, v35, v29
	v_div_fixup_f32 v28, v28, v30, v36
	v_lshlrev_b32_e32 v30, 16, v100
	v_mul_f32_e32 v29, 0xbfb8aa3b, v30
	v_exp_f32_e32 v34, v29
	v_mul_f32_e32 v28, v31, v28
	v_cvt_pk_bf16_f32 v31, v28, s0
	v_lshl_add_u64 v[28:29], v[42:43], 0, v[32:33]
	v_add_f32_e32 v32, 1.0, v34
	v_div_scale_f32 v33, s[16:17], v32, v32, v30
	v_rcp_f32_e32 v34, v33
	global_store_short v[28:29], v31, off
	v_or_b32_e32 v28, 0x50, v48
	v_ashrrev_i32_e32 v29, 31, v28
	v_fma_f32 v31, -v33, v34, 1.0
	v_fmac_f32_e32 v34, v31, v34
	v_div_scale_f32 v31, vcc, v30, v32, v30
	v_mul_f32_e32 v35, v31, v34
	v_fma_f32 v36, -v33, v35, v31
	v_fmac_f32_e32 v35, v36, v34
	v_fma_f32 v31, -v33, v35, v31
	v_lshlrev_b32_e32 v33, 16, v104
	v_div_fmas_f32 v31, v31, v34, v35
	v_mul_f32_e32 v34, 0xbfb8aa3b, v33
	v_exp_f32_e32 v34, v34
	v_div_fixup_f32 v30, v31, v32, v30
	v_mul_f32_e32 v24, v24, v30
	v_lshlrev_b64 v[28:29], 1, v[28:29]
	v_add_f32_e32 v32, 1.0, v34
	v_div_scale_f32 v34, s[16:17], v32, v32, v33
	v_rcp_f32_e32 v35, v34
	v_cvt_pk_bf16_f32 v24, v24, s0
	v_lshl_add_u64 v[30:31], v[44:45], 0, v[28:29]
	global_store_short v[30:31], v24, off
	v_fma_f32 v24, -v34, v35, 1.0
	v_fmac_f32_e32 v35, v24, v35
	v_div_scale_f32 v24, vcc, v33, v32, v33
	v_mul_f32_e32 v30, v24, v35
	v_fma_f32 v31, -v34, v30, v24
	v_fmac_f32_e32 v30, v31, v35
	v_lshlrev_b32_e32 v31, 16, v113
	v_fma_f32 v24, -v34, v30, v24
	v_mul_f32_e32 v34, 0xbfb8aa3b, v31
	v_exp_f32_e32 v34, v34
	v_div_fmas_f32 v24, v24, v35, v30
	v_div_fixup_f32 v24, v24, v32, v33
	v_mul_f32_e32 v24, v25, v24
	v_add_f32_e32 v30, 1.0, v34
	v_div_scale_f32 v32, s[16:17], v30, v30, v31
	v_rcp_f32_e32 v33, v32
	v_cvt_pk_bf16_f32 v34, v24, s0
	v_lshl_add_u64 v[24:25], v[40:41], 0, v[28:29]
	global_store_short v[24:25], v34, off
	v_fma_f32 v24, -v32, v33, 1.0
	v_fmac_f32_e32 v33, v24, v33
	v_div_scale_f32 v24, vcc, v31, v30, v31
	v_mul_f32_e32 v25, v24, v33
	v_fma_f32 v34, -v32, v25, v24
	v_fmac_f32_e32 v25, v34, v33
	v_fma_f32 v24, -v32, v25, v24
	s_waitcnt vmcnt(22)
	v_lshlrev_b32_e32 v32, 16, v77
	v_mul_f32_e32 v34, 0xbfb8aa3b, v32
	v_exp_f32_e32 v34, v34
	v_div_fmas_f32 v24, v24, v33, v25
	v_div_fixup_f32 v24, v24, v30, v31
	v_mul_f32_e32 v24, v26, v24
	v_add_f32_e32 v26, 1.0, v34
	v_div_scale_f32 v30, s[16:17], v26, v26, v32
	v_rcp_f32_e32 v31, v30
	v_cvt_pk_bf16_f32 v33, v24, s0
	v_lshl_add_u64 v[24:25], v[46:47], 0, v[28:29]
	global_store_short v[24:25], v33, off
	v_fma_f32 v24, -v30, v31, 1.0
	v_fmac_f32_e32 v31, v24, v31
	v_div_scale_f32 v24, vcc, v32, v26, v32
	v_mul_f32_e32 v25, v24, v31
	v_fma_f32 v33, -v30, v25, v24
	v_fmac_f32_e32 v25, v33, v31
	v_fma_f32 v24, -v30, v25, v24
	v_div_fmas_f32 v24, v24, v31, v25
	v_div_fixup_f32 v24, v24, v26, v32
	v_lshlrev_b32_e32 v26, 16, v101
	v_mul_f32_e32 v25, 0xbfb8aa3b, v26
	v_exp_f32_e32 v30, v25
	v_mul_f32_e32 v24, v27, v24
	v_cvt_pk_bf16_f32 v27, v24, s0
	v_lshl_add_u64 v[24:25], v[42:43], 0, v[28:29]
	v_add_f32_e32 v28, 1.0, v30
	v_div_scale_f32 v29, s[16:17], v28, v28, v26
	v_rcp_f32_e32 v30, v29
	global_store_short v[24:25], v27, off
	v_or_b32_e32 v24, 0x60, v48
	v_ashrrev_i32_e32 v25, 31, v24
	v_fma_f32 v27, -v29, v30, 1.0
	v_fmac_f32_e32 v30, v27, v30
	v_div_scale_f32 v27, vcc, v26, v28, v26
	v_mul_f32_e32 v31, v27, v30
	v_fma_f32 v32, -v29, v31, v27
	v_fmac_f32_e32 v31, v32, v30
	v_fma_f32 v27, -v29, v31, v27
	v_lshlrev_b32_e32 v29, 16, v103
	v_div_fmas_f32 v27, v27, v30, v31
	v_mul_f32_e32 v30, 0xbfb8aa3b, v29
	v_exp_f32_e32 v30, v30
	v_div_fixup_f32 v26, v27, v28, v26
	v_mul_f32_e32 v20, v20, v26
	v_lshlrev_b64 v[24:25], 1, v[24:25]
	v_add_f32_e32 v28, 1.0, v30
	v_div_scale_f32 v30, s[16:17], v28, v28, v29
	v_rcp_f32_e32 v31, v30
	v_cvt_pk_bf16_f32 v20, v20, s0
	v_lshl_add_u64 v[26:27], v[44:45], 0, v[24:25]
	global_store_short v[26:27], v20, off
	v_fma_f32 v20, -v30, v31, 1.0
	v_fmac_f32_e32 v31, v20, v31
	v_div_scale_f32 v20, vcc, v29, v28, v29
	v_mul_f32_e32 v26, v20, v31
	v_fma_f32 v27, -v30, v26, v20
	v_fmac_f32_e32 v26, v27, v31
	v_lshlrev_b32_e32 v27, 16, v74
	v_fma_f32 v20, -v30, v26, v20
	v_mul_f32_e32 v30, 0xbfb8aa3b, v27
	v_exp_f32_e32 v30, v30
	v_div_fmas_f32 v20, v20, v31, v26
	v_div_fixup_f32 v20, v20, v28, v29
	v_mul_f32_e32 v20, v21, v20
	v_add_f32_e32 v26, 1.0, v30
	v_div_scale_f32 v28, s[16:17], v26, v26, v27
	v_rcp_f32_e32 v29, v28
	v_cvt_pk_bf16_f32 v30, v20, s0
	v_lshl_add_u64 v[20:21], v[40:41], 0, v[24:25]
	global_store_short v[20:21], v30, off
	v_fma_f32 v20, -v28, v29, 1.0
	v_fmac_f32_e32 v29, v20, v29
	v_div_scale_f32 v20, vcc, v27, v26, v27
	v_mul_f32_e32 v21, v20, v29
	v_fma_f32 v30, -v28, v21, v20
	v_fmac_f32_e32 v21, v30, v29
	v_fma_f32 v20, -v28, v21, v20
	s_waitcnt vmcnt(25)
	v_lshlrev_b32_e32 v28, 16, v62
	v_mul_f32_e32 v30, 0xbfb8aa3b, v28
	v_exp_f32_e32 v30, v30
	v_div_fmas_f32 v20, v20, v29, v21
	v_div_fixup_f32 v20, v20, v26, v27
	v_mul_f32_e32 v20, v22, v20
	v_add_f32_e32 v22, 1.0, v30
	v_div_scale_f32 v26, s[16:17], v22, v22, v28
	v_rcp_f32_e32 v27, v26
	v_cvt_pk_bf16_f32 v29, v20, s0
	v_lshl_add_u64 v[20:21], v[46:47], 0, v[24:25]
	global_store_short v[20:21], v29, off
	v_fma_f32 v20, -v26, v27, 1.0
	v_fmac_f32_e32 v27, v20, v27
	v_div_scale_f32 v20, vcc, v28, v22, v28
	v_mul_f32_e32 v21, v20, v27
	v_fma_f32 v29, -v26, v21, v20
	v_fmac_f32_e32 v21, v29, v27
	v_fma_f32 v20, -v26, v21, v20
	v_div_fmas_f32 v20, v20, v27, v21
	v_div_fixup_f32 v20, v20, v22, v28
	v_lshlrev_b32_e32 v22, 16, v102
	v_mul_f32_e32 v21, 0xbfb8aa3b, v22
	v_exp_f32_e32 v26, v21
	v_mul_f32_e32 v20, v23, v20
	v_cvt_pk_bf16_f32 v23, v20, s0
	v_lshl_add_u64 v[20:21], v[42:43], 0, v[24:25]
	v_add_f32_e32 v24, 1.0, v26
	v_div_scale_f32 v25, s[16:17], v24, v24, v22
	v_rcp_f32_e32 v26, v25
	global_store_short v[20:21], v23, off
	v_or_b32_e32 v20, 0x70, v48
	v_ashrrev_i32_e32 v21, 31, v20
	v_fma_f32 v23, -v25, v26, 1.0
	v_fmac_f32_e32 v26, v23, v26
	v_div_scale_f32 v23, vcc, v22, v24, v22
	v_mul_f32_e32 v27, v23, v26
	v_fma_f32 v28, -v25, v27, v23
	v_fmac_f32_e32 v27, v28, v26
	v_fma_f32 v23, -v25, v27, v23
	v_lshlrev_b32_e32 v25, 16, v66
	v_div_fmas_f32 v23, v23, v26, v27
	v_mul_f32_e32 v26, 0xbfb8aa3b, v25
	v_exp_f32_e32 v26, v26
	v_div_fixup_f32 v22, v23, v24, v22
	v_mul_f32_e32 v16, v16, v22
	v_lshlrev_b64 v[20:21], 1, v[20:21]
	v_add_f32_e32 v24, 1.0, v26
	v_div_scale_f32 v26, s[16:17], v24, v24, v25
	v_rcp_f32_e32 v27, v26
	v_cvt_pk_bf16_f32 v16, v16, s0
	v_lshl_add_u64 v[22:23], v[44:45], 0, v[20:21]
	global_store_short v[22:23], v16, off
	v_fma_f32 v16, -v26, v27, 1.0
	v_fmac_f32_e32 v27, v16, v27
	v_div_scale_f32 v16, vcc, v25, v24, v25
	v_mul_f32_e32 v22, v16, v27
	v_fma_f32 v23, -v26, v22, v16
	v_fmac_f32_e32 v22, v23, v27
	v_lshlrev_b32_e32 v23, 16, v67
	v_fma_f32 v16, -v26, v22, v16
	v_mul_f32_e32 v26, 0xbfb8aa3b, v23
	v_exp_f32_e32 v26, v26
	v_div_fmas_f32 v16, v16, v27, v22
	v_div_fixup_f32 v16, v16, v24, v25
	v_mul_f32_e32 v16, v17, v16
	v_add_f32_e32 v22, 1.0, v26
	v_div_scale_f32 v24, s[16:17], v22, v22, v23
	v_rcp_f32_e32 v25, v24
	v_cvt_pk_bf16_f32 v26, v16, s0
	v_lshl_add_u64 v[16:17], v[40:41], 0, v[20:21]
	global_store_short v[16:17], v26, off
	v_fma_f32 v16, -v24, v25, 1.0
	v_fmac_f32_e32 v25, v16, v25
	v_div_scale_f32 v16, vcc, v23, v22, v23
	v_mul_f32_e32 v17, v16, v25
	v_fma_f32 v26, -v24, v17, v16
	v_fmac_f32_e32 v17, v26, v25
	v_fma_f32 v16, -v24, v17, v16
	s_waitcnt vmcnt(28)
	v_lshlrev_b32_e32 v24, 16, v49
	v_mul_f32_e32 v26, 0xbfb8aa3b, v24
	v_exp_f32_e32 v26, v26
	v_div_fmas_f32 v16, v16, v25, v17
	v_div_fixup_f32 v16, v16, v22, v23
	v_mul_f32_e32 v16, v18, v16
	v_add_f32_e32 v18, 1.0, v26
	v_div_scale_f32 v22, s[16:17], v18, v18, v24
	v_rcp_f32_e32 v23, v22
	v_cvt_pk_bf16_f32 v25, v16, s0
	v_lshl_add_u64 v[16:17], v[46:47], 0, v[20:21]
	global_store_short v[16:17], v25, off
	v_fma_f32 v16, -v22, v23, 1.0
	v_fmac_f32_e32 v23, v16, v23
	v_div_scale_f32 v16, vcc, v24, v18, v24
	v_mul_f32_e32 v17, v16, v23
	v_fma_f32 v25, -v22, v17, v16
	v_fmac_f32_e32 v17, v25, v23
	v_fma_f32 v16, -v22, v17, v16
	v_div_fmas_f32 v16, v16, v23, v17
	v_div_fixup_f32 v16, v16, v18, v24
	v_mul_f32_e32 v16, v19, v16
	v_cvt_pk_bf16_f32 v18, v16, s0
	v_lshl_add_u64 v[16:17], v[42:43], 0, v[20:21]
	global_store_short v[16:17], v18, off
	s_branch .LBB0_862

.LBB0_907:
	s_or_b64 exec, exec, s[8:9]
	s_andn2_b64 vcc, exec, s[28:29]
	v_readfirstlane_b32 s3, v196
	s_cbranch_vccnz .LBB0_931
	s_ashr_i32 s8, s2, 31
	s_lshr_b32 s8, s8, 29
	s_add_i32 s8, s2, s8
	s_lshr_b32 s12, s3, 6
	s_ashr_i32 s9, s8, 3
	s_and_b32 s8, s8, -8
	s_lshr_b32 s15, s3, 8
	s_lshl_b32 s33, s12, 10
	s_sub_i32 s8, s2, s8
	s_cmp_lt_i32 s8, 0
	s_movk_i32 s35, 0x42
	s_cselect_b32 s10, s35, 0x41
	s_mul_i32 s8, s8, s10
	s_add_i32 s8, s8, s9
	s_ashr_i32 s9, s8, 31
	s_lshr_b32 s9, s9, 26
	s_add_i32 s9, s8, s9
	s_ashr_i32 s10, s9, 6
	s_lshl_b32 s10, s10, 3
	s_sub_i32 s11, 0x41, s10
	s_min_u32 s11, s11, 8
	s_andn2_b32 s9, s9, 63
	s_sub_i32 s13, s8, s9
	v_cvt_f32_ubyte0_e32 v1, s11
	v_cvt_f32_i32_e32 v0, s13
	v_rcp_iflag_f32_e32 v2, v1
	s_ashr_i32 s8, s13, 30
	s_or_b32 s14, s8, 1
	s_mov_b32 s61, 0
	v_mul_f32_e32 v2, v0, v2
	v_trunc_f32_e32 v2, v2
	v_fma_f32 v0, -v2, v1, v0
	v_cvt_i32_f32_e32 v2, v2
	v_cmp_ge_f32_e64 s[8:9], |v0|, v1
	s_and_b64 s[8:9], s[8:9], exec
	s_cselect_b32 s8, s14, 0
	v_readfirstlane_b32 s9, v2
	s_add_i32 s14, s9, s8
	s_mul_i32 s8, s14, s11
	s_sub_i32 s8, s13, s8
	s_sext_i32_i8 s8, s8
	s_add_i32 s38, s10, s8
	s_ashr_i32 s39, s38, 31
	s_lshl_b64 s[8:9], s[38:39], 20
	s_add_u32 s8, s24, s8
	s_addc_u32 s9, s25, s9
	s_bfe_i64 s[10:11], s[14:15], 0x80000
	s_lshl_b64 s[10:11], s[10:11], 20
	s_add_u32 s52, s36, s10
	s_addc_u32 s53, s37, s11
	s_add_i32 s39, s33, 0
	s_add_i32 m0, s39, 0x10000
	s_add_i32 s56, s39, 0x2000
	global_load_lds_dwordx4 v202, s[52:53]
	s_add_i32 m0, s39, 0x12000
	s_add_u32 s10, s52, 0x80000
	global_load_lds_dwordx4 v204, s[52:53]
	s_mov_b32 m0, s39
	s_addc_u32 s11, s53, 0
	global_load_lds_dwordx4 v202, s[8:9]
	s_mov_b32 m0, s56
	s_add_i32 s57, s39, 0x14000
	global_load_lds_dwordx4 v204, s[8:9]
	s_mov_b32 m0, s57
	s_add_i32 s58, s39, 0x16000
	global_load_lds_dwordx4 v202, s[10:11]
	s_mov_b32 m0, s58
	v_mov_b32_e32 v0, 0
	global_load_lds_dwordx4 v204, s[10:11]
	s_add_u32 s10, s8, 0x80000
	s_addc_u32 s11, s9, 0
	s_add_i32 s59, s39, 0x4000
	s_mov_b32 m0, s59
	s_add_i32 s60, s39, 0x6000
	global_load_lds_dwordx4 v202, s[10:11]
	s_mov_b32 m0, s60
	v_mov_b32_e32 v203, v0
	global_load_lds_dwordx4 v204, s[10:11]
	v_mov_b32_e32 v205, v0
	v_lshl_add_u64 v[8:9], s[52:53], 0, v[202:203]
	v_lshl_add_u64 v[6:7], s[52:53], 0, v[204:205]
	v_lshl_add_u64 v[4:5], s[8:9], 0, v[202:203]
	v_lshl_add_u64 v[2:3], s[8:9], 0, v[204:205]
	s_cmp_lg_u32 s15, 1
	s_mov_b64 s[10:11], 0x80000
	s_cbranch_scc1 .LBB0_910
	s_barrier

.LBB0_943:
	s_or_b64 exec, exec, s[0:1]
	s_and_saveexec_b64 s[0:1], s[6:7]
	s_cbranch_execz .LBB0_946
	v_and_b32_e32 v0, 64, v201
	v_add_u32_e32 v0, 64, v0
	v_xor_b32_e32 v1, 32, v201
	v_cmp_lt_i32_e32 vcc, v1, v0
	v_and_b32_e32 v14, 0xfc, v226
	v_or_b32_e32 v16, 0x400, v14
	v_cndmask_b32_e32 v1, v201, v1, vcc
	v_lshlrev_b32_e32 v26, 2, v1
	v_xor_b32_e32 v1, 16, v201
	v_cmp_lt_i32_e32 vcc, v1, v0
	v_or_b32_e32 v18, 0x500, v14
	v_or_b32_e32 v20, 0x600, v14
	v_cndmask_b32_e32 v1, v201, v1, vcc
	v_lshlrev_b32_e32 v27, 2, v1
	v_xor_b32_e32 v1, 8, v201
	v_cmp_lt_i32_e32 vcc, v1, v0
	v_or_b32_e32 v22, 0x700, v14
	s_lshl_b32 s2, s34, 3
	v_cndmask_b32_e32 v1, v201, v1, vcc
	v_lshlrev_b32_e32 v28, 2, v1
	v_xor_b32_e32 v1, 4, v201
	v_cmp_lt_i32_e32 vcc, v1, v0
	s_mov_b64 s[0:1], 0
	v_mov_b32_e32 v32, 0x358637bd
	v_cndmask_b32_e32 v1, v201, v1, vcc
	v_lshlrev_b32_e32 v29, 2, v1
	v_xor_b32_e32 v1, 2, v201
	v_cmp_lt_i32_e32 vcc, v1, v0
	s_mov_b32 s3, 0x800000
	s_movk_i32 s4, 0x407f
	v_cndmask_b32_e32 v1, v201, v1, vcc
	v_lshlrev_b32_e32 v30, 2, v1
	v_xor_b32_e32 v1, 1, v201
	v_cmp_lt_i32_e32 vcc, v1, v0
	s_nop 1
	v_cndmask_b32_e32 v0, v201, v1, vcc
	v_lshlrev_b32_e32 v31, 2, v0
	v_mov_b32_e32 v1, 0
	v_lshlrev_b32_e32 v0, 2, v14
	v_lshl_add_u64 v[2:3], s[42:43], 0, v[0:1]
	v_lshlrev_b32_e32 v0, 2, v16
	v_lshl_add_u64 v[4:5], s[42:43], 0, v[0:1]
	v_lshlrev_b32_e32 v0, 2, v18
	v_lshl_add_u64 v[6:7], s[42:43], 0, v[0:1]
	v_lshlrev_b32_e32 v0, 2, v20
	v_lshl_add_u64 v[8:9], s[42:43], 0, v[0:1]
	v_lshlrev_b32_e32 v0, 2, v22
	v_lshl_add_u64 v[10:11], s[42:43], 0, v[0:1]
	v_lshlrev_b32_e32 v0, 1, v14
	v_lshl_add_u64 v[12:13], s[26:27], 0, v[0:1]
	v_lshlrev_b32_e32 v0, 2, v14
	v_lshlrev_b32_e32 v14, 2, v16
	v_mov_b32_e32 v15, v1
	v_lshlrev_b32_e32 v16, 2, v18
	v_mov_b32_e32 v17, v1
	v_lshlrev_b32_e32 v18, 2, v20
	v_mov_b32_e32 v19, v1
	v_lshlrev_b32_e32 v20, 2, v22
	v_mov_b32_e32 v21, v1
	global_load_dwordx4 v[64:67], v[2:3], off
	global_load_dwordx4 v[68:71], v[2:3], off offset:1024
	global_load_dwordx4 v[72:75], v[2:3], off offset:2048
	global_load_dwordx4 v[76:79], v[2:3], off offset:3072
	global_load_dwordx4 v[80:83], v[4:5], off
	global_load_dwordx4 v[84:87], v[6:7], off
	global_load_dwordx4 v[88:91], v[8:9], off
	global_load_dwordx4 v[92:95], v[10:11], off
	v_lshrrev_b32_e32 v60, 1, v0
	v_add_u32_e32 v62, 0x1000, v0
	v_readfirstlane_b32 s21, v200
	s_lshl_b32 s20, s21, 12
	s_add_u32 s10, s26, s20
	s_addc_u32 s11, s27, 0
	s_lshl_b32 s20, s21, 13
	s_add_u32 s12, s48, s20
	s_addc_u32 s13, s49, 0
	global_load_dwordx2 v[96:97], v60, s[10:11] offset:0
	global_load_dwordx2 v[98:99], v60, s[10:11] offset:512
	global_load_dwordx2 v[100:101], v60, s[10:11] offset:1024
	global_load_dwordx2 v[102:103], v60, s[10:11] offset:1536
	global_load_dwordx2 v[104:105], v60, s[10:11] offset:2048
	global_load_dwordx2 v[106:107], v60, s[10:11] offset:2560
	global_load_dwordx2 v[108:109], v60, s[10:11] offset:3072
	global_load_dwordx2 v[110:111], v60, s[10:11] offset:3584
	global_load_dwordx4 v[112:115], v0, s[12:13] offset:0
	global_load_dwordx4 v[116:119], v0, s[12:13] offset:1024
	global_load_dwordx4 v[120:123], v0, s[12:13] offset:2048
	global_load_dwordx4 v[124:127], v0, s[12:13] offset:3072
	global_load_dwordx4 v[128:131], v62, s[12:13] offset:0
	global_load_dwordx4 v[132:135], v62, s[12:13] offset:1024
	global_load_dwordx4 v[136:139], v62, s[12:13] offset:2048
	global_load_dwordx4 v[140:143], v62, s[12:13] offset:3072
	global_load_dwordx4 v[224:227], v[2:3], off
	global_load_dwordx4 v[228:231], v[2:3], off
	global_load_dwordx4 v[232:235], v[2:3], off
	global_load_dwordx4 v[236:239], v[2:3], off
	global_load_dwordx4 v[240:243], v[2:3], off
	global_load_dwordx4 v[244:247], v[2:3], off
	global_load_dwordx4 v[248:251], v[2:3], off
	global_load_dwordx4 v[252:255], v[2:3], off
.Lp10_loop:
	s_add_u32 s22, s21, s2
	s_min_u32 s23, s22, s4
	s_lshl_b32 s20, s23, 12
	s_add_u32 s14, s26, s20
	s_addc_u32 s15, s27, 0
	s_lshl_b32 s20, s23, 13
	s_add_u32 s16, s48, s20
	s_addc_u32 s17, s49, 0
	global_load_dwordx2 v[144:145], v60, s[14:15] offset:0
	global_load_dwordx2 v[146:147], v60, s[14:15] offset:512
	global_load_dwordx2 v[148:149], v60, s[14:15] offset:1024
	global_load_dwordx2 v[150:151], v60, s[14:15] offset:1536
	global_load_dwordx2 v[152:153], v60, s[14:15] offset:2048
	global_load_dwordx2 v[154:155], v60, s[14:15] offset:2560
	global_load_dwordx2 v[156:157], v60, s[14:15] offset:3072
	global_load_dwordx2 v[158:159], v60, s[14:15] offset:3584
	global_load_dwordx4 v[160:163], v0, s[16:17] offset:0
	global_load_dwordx4 v[164:167], v0, s[16:17] offset:1024
	global_load_dwordx4 v[168:171], v0, s[16:17] offset:2048
	global_load_dwordx4 v[172:175], v0, s[16:17] offset:3072
	global_load_dwordx4 v[176:179], v62, s[16:17] offset:0
	global_load_dwordx4 v[180:183], v62, s[16:17] offset:1024
	global_load_dwordx4 v[184:187], v62, s[16:17] offset:2048
	global_load_dwordx4 v[188:191], v62, s[16:17] offset:3072
	s_waitcnt vmcnt(32)
	v_lshlrev_b32_e32 v192, 16, v96
	v_and_b32_e32 v193, 0xffff0000, v96
	v_lshlrev_b32_e32 v194, 16, v97
	v_and_b32_e32 v195, 0xffff0000, v97
	v_lshlrev_b32_e32 v196, 16, v98
	v_and_b32_e32 v197, 0xffff0000, v98
	v_lshlrev_b32_e32 v198, 16, v99
	v_and_b32_e32 v199, 0xffff0000, v99
	v_lshlrev_b32_e32 v200, 16, v100
	v_and_b32_e32 v201, 0xffff0000, v100
	v_lshlrev_b32_e32 v202, 16, v101
	v_and_b32_e32 v203, 0xffff0000, v101
	v_lshlrev_b32_e32 v204, 16, v102
	v_and_b32_e32 v205, 0xffff0000, v102
	v_lshlrev_b32_e32 v206, 16, v103
	v_and_b32_e32 v207, 0xffff0000, v103
	v_lshlrev_b32_e32 v208, 16, v104
	v_and_b32_e32 v209, 0xffff0000, v104
	v_lshlrev_b32_e32 v210, 16, v105
	v_and_b32_e32 v211, 0xffff0000, v105
	v_lshlrev_b32_e32 v212, 16, v106
	v_and_b32_e32 v213, 0xffff0000, v106
	v_lshlrev_b32_e32 v214, 16, v107
	v_and_b32_e32 v215, 0xffff0000, v107
	v_lshlrev_b32_e32 v216, 16, v108
	v_and_b32_e32 v217, 0xffff0000, v108
	v_lshlrev_b32_e32 v218, 16, v109
	v_and_b32_e32 v219, 0xffff0000, v109
	v_lshlrev_b32_e32 v220, 16, v110
	v_and_b32_e32 v221, 0xffff0000, v110
	v_lshlrev_b32_e32 v222, 16, v111
	v_and_b32_e32 v223, 0xffff0000, v111
	v_mul_f32_e32 v34, v192, v192
	v_mul_f32_e32 v35, v193, v193
	v_mul_f32_e32 v36, v194, v194
	v_mul_f32_e32 v37, v195, v195
	v_fmac_f32_e32 v34, v196, v196
	v_fmac_f32_e32 v35, v197, v197
	v_fmac_f32_e32 v36, v198, v198
	v_fmac_f32_e32 v37, v199, v199
	v_fmac_f32_e32 v34, v200, v200
	v_fmac_f32_e32 v35, v201, v201
	v_fmac_f32_e32 v36, v202, v202
	v_fmac_f32_e32 v37, v203, v203
	v_fmac_f32_e32 v34, v204, v204
	v_fmac_f32_e32 v35, v205, v205
	v_fmac_f32_e32 v36, v206, v206
	v_fmac_f32_e32 v37, v207, v207
	v_fmac_f32_e32 v34, v208, v208
	v_fmac_f32_e32 v35, v209, v209
	v_fmac_f32_e32 v36, v210, v210
	v_fmac_f32_e32 v37, v211, v211
	v_fmac_f32_e32 v34, v212, v212
	v_fmac_f32_e32 v35, v213, v213
	v_fmac_f32_e32 v36, v214, v214
	v_fmac_f32_e32 v37, v215, v215
	v_fmac_f32_e32 v34, v216, v216
	v_fmac_f32_e32 v35, v217, v217
	v_fmac_f32_e32 v36, v218, v218
	v_fmac_f32_e32 v37, v219, v219
	v_fmac_f32_e32 v34, v220, v220
	v_fmac_f32_e32 v35, v221, v221
	v_fmac_f32_e32 v36, v222, v222
	v_fmac_f32_e32 v37, v223, v223
	v_add_f32_e32 v34, v34, v35
	v_add_f32_e32 v36, v36, v37
	v_add_f32_e32 v33, v34, v36
	ds_bpermute_b32 v42, v26, v33
	s_waitcnt lgkmcnt(0)
	v_add_f32_e32 v33, v33, v42
	ds_bpermute_b32 v42, v27, v33
	s_waitcnt lgkmcnt(0)
	v_add_f32_e32 v33, v33, v42
	ds_bpermute_b32 v42, v28, v33
	s_waitcnt lgkmcnt(0)
	v_add_f32_e32 v33, v33, v42
	ds_bpermute_b32 v42, v29, v33
	s_waitcnt lgkmcnt(0)
	v_add_f32_e32 v33, v33, v42
	ds_bpermute_b32 v42, v30, v33
	s_waitcnt lgkmcnt(0)
	v_add_f32_e32 v33, v33, v42
	ds_bpermute_b32 v42, v31, v33
	s_waitcnt lgkmcnt(0)
	v_add_f32_e32 v33, v33, v42
	v_fmamk_f32 v33, v33, 0x3a000000, v32
	v_mul_f32_e32 v42, 0x4b800000, v33
	v_cmp_gt_f32_e32 vcc, s3, v33
	s_nop 1
	v_cndmask_b32_e32 v33, v33, v42, vcc
	v_rsq_f32_e32 v33, v33
	s_nop 0
	v_mul_f32_e32 v54, 0x45800000, v33
	v_cndmask_b32_e32 v54, v33, v54, vcc
	v_pk_mul_f32 v[192:193], v[192:193], v[54:55] op_sel_hi:[1,0]
	v_pk_mul_f32 v[194:195], v[194:195], v[54:55] op_sel_hi:[1,0]
	v_pk_mul_f32 v[196:197], v[196:197], v[54:55] op_sel_hi:[1,0]
	v_pk_mul_f32 v[198:199], v[198:199], v[54:55] op_sel_hi:[1,0]
	v_pk_mul_f32 v[200:201], v[200:201], v[54:55] op_sel_hi:[1,0]
	v_pk_mul_f32 v[202:203], v[202:203], v[54:55] op_sel_hi:[1,0]
	v_pk_mul_f32 v[204:205], v[204:205], v[54:55] op_sel_hi:[1,0]
	v_pk_mul_f32 v[206:207], v[206:207], v[54:55] op_sel_hi:[1,0]
	v_pk_mul_f32 v[208:209], v[208:209], v[54:55] op_sel_hi:[1,0]
	v_pk_mul_f32 v[210:211], v[210:211], v[54:55] op_sel_hi:[1,0]
	v_pk_mul_f32 v[212:213], v[212:213], v[54:55] op_sel_hi:[1,0]
	v_pk_mul_f32 v[214:215], v[214:215], v[54:55] op_sel_hi:[1,0]
	v_pk_mul_f32 v[216:217], v[216:217], v[54:55] op_sel_hi:[1,0]
	v_pk_mul_f32 v[218:219], v[218:219], v[54:55] op_sel_hi:[1,0]
	v_pk_mul_f32 v[220:221], v[220:221], v[54:55] op_sel_hi:[1,0]
	v_pk_mul_f32 v[222:223], v[222:223], v[54:55] op_sel_hi:[1,0]
	s_waitcnt vmcnt(24)
	v_pk_fma_f32 v[112:113], v[64:65], v[192:193], v[112:113]
	v_pk_fma_f32 v[114:115], v[66:67], v[194:195], v[114:115]
	v_pk_fma_f32 v[116:117], v[68:69], v[196:197], v[116:117]
	v_pk_fma_f32 v[118:119], v[70:71], v[198:199], v[118:119]
	v_pk_fma_f32 v[120:121], v[72:73], v[200:201], v[120:121]
	v_pk_fma_f32 v[122:123], v[74:75], v[202:203], v[122:123]
	v_pk_fma_f32 v[124:125], v[76:77], v[204:205], v[124:125]
	v_pk_fma_f32 v[126:127], v[78:79], v[206:207], v[126:127]
	v_pk_fma_f32 v[128:129], v[80:81], v[208:209], v[128:129]
	v_pk_fma_f32 v[130:131], v[82:83], v[210:211], v[130:131]
	v_pk_fma_f32 v[132:133], v[84:85], v[212:213], v[132:133]
	v_pk_fma_f32 v[134:135], v[86:87], v[214:215], v[134:135]
	v_pk_fma_f32 v[136:137], v[88:89], v[216:217], v[136:137]
	v_pk_fma_f32 v[138:139], v[90:91], v[218:219], v[138:139]
	v_pk_fma_f32 v[140:141], v[92:93], v[220:221], v[140:141]
	v_pk_fma_f32 v[142:143], v[94:95], v[222:223], v[142:143]
	global_store_dwordx4 v0, v[112:115], s[12:13] offset:0
	global_store_dwordx4 v0, v[116:119], s[12:13] offset:1024
	global_store_dwordx4 v0, v[120:123], s[12:13] offset:2048
	global_store_dwordx4 v0, v[124:127], s[12:13] offset:3072
	global_store_dwordx4 v62, v[128:131], s[12:13] offset:0
	global_store_dwordx4 v62, v[132:135], s[12:13] offset:1024
	global_store_dwordx4 v62, v[136:139], s[12:13] offset:2048
	global_store_dwordx4 v62, v[140:143], s[12:13] offset:3072
	s_mov_b32 s21, s22
	s_cmp_gt_u32 s21, s4
	s_cbranch_scc1 .Lp10_done
	s_add_u32 s22, s21, s2
	s_min_u32 s23, s22, s4
	s_lshl_b32 s20, s23, 12
	s_add_u32 s10, s26, s20
	s_addc_u32 s11, s27, 0
	s_lshl_b32 s20, s23, 13
	s_add_u32 s12, s48, s20
	s_addc_u32 s13, s49, 0
	global_load_dwordx2 v[96:97], v60, s[10:11] offset:0
	global_load_dwordx2 v[98:99], v60, s[10:11] offset:512
	global_load_dwordx2 v[100:101], v60, s[10:11] offset:1024
	global_load_dwordx2 v[102:103], v60, s[10:11] offset:1536
	global_load_dwordx2 v[104:105], v60, s[10:11] offset:2048
	global_load_dwordx2 v[106:107], v60, s[10:11] offset:2560
	global_load_dwordx2 v[108:109], v60, s[10:11] offset:3072
	global_load_dwordx2 v[110:111], v60, s[10:11] offset:3584
	global_load_dwordx4 v[112:115], v0, s[12:13] offset:0
	global_load_dwordx4 v[116:119], v0, s[12:13] offset:1024
	global_load_dwordx4 v[120:123], v0, s[12:13] offset:2048
	global_load_dwordx4 v[124:127], v0, s[12:13] offset:3072
	global_load_dwordx4 v[128:131], v62, s[12:13] offset:0
	global_load_dwordx4 v[132:135], v62, s[12:13] offset:1024
	global_load_dwordx4 v[136:139], v62, s[12:13] offset:2048
	global_load_dwordx4 v[140:143], v62, s[12:13] offset:3072
	s_waitcnt vmcnt(32)
	v_lshlrev_b32_e32 v192, 16, v144
	v_and_b32_e32 v193, 0xffff0000, v144
	v_lshlrev_b32_e32 v194, 16, v145
	v_and_b32_e32 v195, 0xffff0000, v145
	v_lshlrev_b32_e32 v196, 16, v146
	v_and_b32_e32 v197, 0xffff0000, v146
	v_lshlrev_b32_e32 v198, 16, v147
	v_and_b32_e32 v199, 0xffff0000, v147
	v_lshlrev_b32_e32 v200, 16, v148
	v_and_b32_e32 v201, 0xffff0000, v148
	v_lshlrev_b32_e32 v202, 16, v149
	v_and_b32_e32 v203, 0xffff0000, v149
	v_lshlrev_b32_e32 v204, 16, v150
	v_and_b32_e32 v205, 0xffff0000, v150
	v_lshlrev_b32_e32 v206, 16, v151
	v_and_b32_e32 v207, 0xffff0000, v151
	v_lshlrev_b32_e32 v208, 16, v152
	v_and_b32_e32 v209, 0xffff0000, v152
	v_lshlrev_b32_e32 v210, 16, v153
	v_and_b32_e32 v211, 0xffff0000, v153
	v_lshlrev_b32_e32 v212, 16, v154
	v_and_b32_e32 v213, 0xffff0000, v154
	v_lshlrev_b32_e32 v214, 16, v155
	v_and_b32_e32 v215, 0xffff0000, v155
	v_lshlrev_b32_e32 v216, 16, v156
	v_and_b32_e32 v217, 0xffff0000, v156
	v_lshlrev_b32_e32 v218, 16, v157
	v_and_b32_e32 v219, 0xffff0000, v157
	v_lshlrev_b32_e32 v220, 16, v158
	v_and_b32_e32 v221, 0xffff0000, v158
	v_lshlrev_b32_e32 v222, 16, v159
	v_and_b32_e32 v223, 0xffff0000, v159
	v_mul_f32_e32 v34, v192, v192
	v_mul_f32_e32 v35, v193, v193
	v_mul_f32_e32 v36, v194, v194
	v_mul_f32_e32 v37, v195, v195
	v_fmac_f32_e32 v34, v196, v196
	v_fmac_f32_e32 v35, v197, v197
	v_fmac_f32_e32 v36, v198, v198
	v_fmac_f32_e32 v37, v199, v199
	v_fmac_f32_e32 v34, v200, v200
	v_fmac_f32_e32 v35, v201, v201
	v_fmac_f32_e32 v36, v202, v202
	v_fmac_f32_e32 v37, v203, v203
	v_fmac_f32_e32 v34, v204, v204
	v_fmac_f32_e32 v35, v205, v205
	v_fmac_f32_e32 v36, v206, v206
	v_fmac_f32_e32 v37, v207, v207
	v_fmac_f32_e32 v34, v208, v208
	v_fmac_f32_e32 v35, v209, v209
	v_fmac_f32_e32 v36, v210, v210
	v_fmac_f32_e32 v37, v211, v211
	v_fmac_f32_e32 v34, v212, v212
	v_fmac_f32_e32 v35, v213, v213
	v_fmac_f32_e32 v36, v214, v214
	v_fmac_f32_e32 v37, v215, v215
	v_fmac_f32_e32 v34, v216, v216
	v_fmac_f32_e32 v35, v217, v217
	v_fmac_f32_e32 v36, v218, v218
	v_fmac_f32_e32 v37, v219, v219
	v_fmac_f32_e32 v34, v220, v220
	v_fmac_f32_e32 v35, v221, v221
	v_fmac_f32_e32 v36, v222, v222
	v_fmac_f32_e32 v37, v223, v223
	v_add_f32_e32 v34, v34, v35
	v_add_f32_e32 v36, v36, v37
	v_add_f32_e32 v33, v34, v36
	ds_bpermute_b32 v42, v26, v33
	s_waitcnt lgkmcnt(0)
	v_add_f32_e32 v33, v33, v42
	ds_bpermute_b32 v42, v27, v33
	s_waitcnt lgkmcnt(0)
	v_add_f32_e32 v33, v33, v42
	ds_bpermute_b32 v42, v28, v33
	s_waitcnt lgkmcnt(0)
	v_add_f32_e32 v33, v33, v42
	ds_bpermute_b32 v42, v29, v33
	s_waitcnt lgkmcnt(0)
	v_add_f32_e32 v33, v33, v42
	ds_bpermute_b32 v42, v30, v33
	s_waitcnt lgkmcnt(0)
	v_add_f32_e32 v33, v33, v42
	ds_bpermute_b32 v42, v31, v33
	s_waitcnt lgkmcnt(0)
	v_add_f32_e32 v33, v33, v42
	v_fmamk_f32 v33, v33, 0x3a000000, v32
	v_mul_f32_e32 v42, 0x4b800000, v33
	v_cmp_gt_f32_e32 vcc, s3, v33
	s_nop 1
	v_cndmask_b32_e32 v33, v33, v42, vcc
	v_rsq_f32_e32 v33, v33
	s_nop 0
	v_mul_f32_e32 v54, 0x45800000, v33
	v_cndmask_b32_e32 v54, v33, v54, vcc
	v_pk_mul_f32 v[192:193], v[192:193], v[54:55] op_sel_hi:[1,0]
	v_pk_mul_f32 v[194:195], v[194:195], v[54:55] op_sel_hi:[1,0]
	v_pk_mul_f32 v[196:197], v[196:197], v[54:55] op_sel_hi:[1,0]
	v_pk_mul_f32 v[198:199], v[198:199], v[54:55] op_sel_hi:[1,0]
	v_pk_mul_f32 v[200:201], v[200:201], v[54:55] op_sel_hi:[1,0]
	v_pk_mul_f32 v[202:203], v[202:203], v[54:55] op_sel_hi:[1,0]
	v_pk_mul_f32 v[204:205], v[204:205], v[54:55] op_sel_hi:[1,0]
	v_pk_mul_f32 v[206:207], v[206:207], v[54:55] op_sel_hi:[1,0]
	v_pk_mul_f32 v[208:209], v[208:209], v[54:55] op_sel_hi:[1,0]
	v_pk_mul_f32 v[210:211], v[210:211], v[54:55] op_sel_hi:[1,0]
	v_pk_mul_f32 v[212:213], v[212:213], v[54:55] op_sel_hi:[1,0]
	v_pk_mul_f32 v[214:215], v[214:215], v[54:55] op_sel_hi:[1,0]
	v_pk_mul_f32 v[216:217], v[216:217], v[54:55] op_sel_hi:[1,0]
	v_pk_mul_f32 v[218:219], v[218:219], v[54:55] op_sel_hi:[1,0]
	v_pk_mul_f32 v[220:221], v[220:221], v[54:55] op_sel_hi:[1,0]
	v_pk_mul_f32 v[222:223], v[222:223], v[54:55] op_sel_hi:[1,0]
	s_waitcnt vmcnt(24)
	v_pk_fma_f32 v[160:161], v[64:65], v[192:193], v[160:161]
	v_pk_fma_f32 v[162:163], v[66:67], v[194:195], v[162:163]
	v_pk_fma_f32 v[164:165], v[68:69], v[196:197], v[164:165]
	v_pk_fma_f32 v[166:167], v[70:71], v[198:199], v[166:167]
	v_pk_fma_f32 v[168:169], v[72:73], v[200:201], v[168:169]
	v_pk_fma_f32 v[170:171], v[74:75], v[202:203], v[170:171]
	v_pk_fma_f32 v[172:173], v[76:77], v[204:205], v[172:173]
	v_pk_fma_f32 v[174:175], v[78:79], v[206:207], v[174:175]
	v_pk_fma_f32 v[176:177], v[80:81], v[208:209], v[176:177]
	v_pk_fma_f32 v[178:179], v[82:83], v[210:211], v[178:179]
	v_pk_fma_f32 v[180:181], v[84:85], v[212:213], v[180:181]
	v_pk_fma_f32 v[182:183], v[86:87], v[214:215], v[182:183]
	v_pk_fma_f32 v[184:185], v[88:89], v[216:217], v[184:185]
	v_pk_fma_f32 v[186:187], v[90:91], v[218:219], v[186:187]
	v_pk_fma_f32 v[188:189], v[92:93], v[220:221], v[188:189]
	v_pk_fma_f32 v[190:191], v[94:95], v[222:223], v[190:191]
	global_store_dwordx4 v0, v[160:163], s[16:17] offset:0
	global_store_dwordx4 v0, v[164:167], s[16:17] offset:1024
	global_store_dwordx4 v0, v[168:171], s[16:17] offset:2048
	global_store_dwordx4 v0, v[172:175], s[16:17] offset:3072
	global_store_dwordx4 v62, v[176:179], s[16:17] offset:0
	global_store_dwordx4 v62, v[180:183], s[16:17] offset:1024
	global_store_dwordx4 v62, v[184:187], s[16:17] offset:2048
	global_store_dwordx4 v62, v[188:191], s[16:17] offset:3072
	s_mov_b32 s21, s22
	s_cmp_le_u32 s21, s4
	s_cbranch_scc1 .Lp10_loop
.Lp10_done:
.LBB0_946:
	s_endpgm
